# chunk attention (XCD path actually executed) online softmax: 16 in-place packed subtracts + 14 packed adds for the row sum instead of 32 + 32 scalar ops
# speedup vs baseline: 1.0077x; 1.0077x over previous
; #define MFMA(a, b, c) __builtin_amdgcn_mfma_f32_32x32x16_bf16((a), (b), (c), 0, 0, 0)
; DI unsigned pack2(float a, float b) { const f32x2 v = {a, b}; return __builtin_bit_cast(unsigned, __builtin_convertvector(v, bf16v2)); }
; DI void attn_item(const Params& p, char* lds, int item) {
;     ...
;       mx = fmaxf(mx, __shfl_xor(mx, 32));
;       const float mnew = fmaxf(mrun, mx);
;       const float alpha = __builtin_amdgcn_exp2f(mrun - mnew);
;       mrun = mnew;
;       float ps = 0.f;
; #pragma unroll
;       for (int sub = 0; sub < 2; ++sub)
; #pragma unroll
;         for (int r = 0; r < 16; ++r) { const float e = __builtin_amdgcn_exp2f(S[sub][r] - mnew); S[sub][r] = e; ps += e; }
;       lrun = lrun * alpha + ps;
; #pragma unroll
;       for (int r = 0; r < 16; ++r) { O[0][r] *= alpha; O[1][r] *= alpha; }
; #pragma unroll
;       for (int sub = 0; sub < 2; ++sub) {
;         bf16x8 Pf[2];
; #pragma unroll
;         for (int ks = 0; ks < 2; ++ks) {
;           union { bf16x8 v; unsigned u[4]; } cv;
;           for (int j2 = 0; j2 < 4; ++j2) cv.u[j2] = pack2(S[sub][8 * ks + 2 * j2], S[sub][8 * ks + 2 * j2 + 1]);
;           Pf[ks] = cv.v;
;         }
;         const u16* vl = Vl + cur * 64 * 72 + l31 * 72 + sub * 32 + 8 * hh;
; #pragma unroll
;         for (int dt = 0; dt < 2; ++dt)
; #pragma unroll
;           for (int ks = 0; ks < 2; ++ks) O[dt] = MFMA(ldfrag(vl + dt * 32 * 72 + 16 * ks), Pf[ks], O[dt]);
;       }
.LBB0_406:
	s_or_b64 exec, exec, s[16:17]
	s_nop 5
	v_and_b32_e32 v49, 64, v114
	v_xor_b32_e32 v48, 32, v114
	v_add_u32_e32 v49, 64, v49
	v_cmp_lt_i32_e32 vcc, v48, v49
	s_nop 1
	v_cndmask_b32_e32 v48, v114, v48, vcc
	v_lshlrev_b32_e32 v48, 2, v48
	ds_bpermute_b32 v48, v48, v0
	s_waitcnt lgkmcnt(0)
	v_max3_f32 v48, v138, v0, v48
	v_pk_add_f32 v[92:93], v[92:93], v[48:49] op_sel_hi:[1,0] neg_lo:[0,1] neg_hi:[0,1]
	v_exp_f32_e32 v49, v92
	v_exp_f32_e32 v51, v93
	v_pk_add_f32 v[88:89], v[88:89], v[48:49] op_sel_hi:[1,0] neg_lo:[0,1] neg_hi:[0,1]
	v_exp_f32_e32 v52, v88
	v_exp_f32_e32 v53, v89
	v_pk_add_f32 v[12:13], v[12:13], v[48:49] op_sel_hi:[1,0] neg_lo:[0,1] neg_hi:[0,1]
	v_exp_f32_e32 v54, v12
	v_exp_f32_e32 v50, v13
	v_pk_add_f32 v[10:11], v[10:11], v[48:49] op_sel_hi:[1,0] neg_lo:[0,1] neg_hi:[0,1]
	v_exp_f32_e32 v55, v10
	v_exp_f32_e32 v11, v11
	v_pk_add_f32 v[96:97], v[96:97], v[48:49] op_sel_hi:[1,0] neg_lo:[0,1] neg_hi:[0,1]
	v_exp_f32_e32 v56, v96
	v_exp_f32_e32 v57, v97
	v_pk_add_f32 v[94:95], v[94:95], v[48:49] op_sel_hi:[1,0] neg_lo:[0,1] neg_hi:[0,1]
	v_exp_f32_e32 v58, v94
	v_exp_f32_e32 v59, v95
	v_pk_add_f32 v[90:91], v[90:91], v[48:49] op_sel_hi:[1,0] neg_lo:[0,1] neg_hi:[0,1]
	v_exp_f32_e32 v60, v90
	v_exp_f32_e32 v61, v91
	v_pk_add_f32 v[14:15], v[14:15], v[48:49] op_sel_hi:[1,0] neg_lo:[0,1] neg_hi:[0,1]
	v_exp_f32_e32 v62, v14
	v_exp_f32_e32 v63, v15
	v_pk_add_f32 v[98:99], v[98:99], v[48:49] op_sel_hi:[1,0] neg_lo:[0,1] neg_hi:[0,1]
	v_exp_f32_e32 v88, v98
	v_exp_f32_e32 v89, v99
	v_pk_add_f32 v[100:101], v[100:101], v[48:49] op_sel_hi:[1,0] neg_lo:[0,1] neg_hi:[0,1]
	v_exp_f32_e32 v90, v100
	v_exp_f32_e32 v91, v101
	v_pk_add_f32 v[102:103], v[102:103], v[48:49] op_sel_hi:[1,0] neg_lo:[0,1] neg_hi:[0,1]
	v_exp_f32_e32 v92, v102
	v_exp_f32_e32 v93, v103
	v_pk_add_f32 v[104:105], v[104:105], v[48:49] op_sel_hi:[1,0] neg_lo:[0,1] neg_hi:[0,1]
	v_exp_f32_e32 v94, v104
	v_exp_f32_e32 v95, v105
	v_pk_add_f32 v[106:107], v[106:107], v[48:49] op_sel_hi:[1,0] neg_lo:[0,1] neg_hi:[0,1]
	v_exp_f32_e32 v96, v106
	v_exp_f32_e32 v97, v107
	v_pk_add_f32 v[108:109], v[108:109], v[48:49] op_sel_hi:[1,0] neg_lo:[0,1] neg_hi:[0,1]
	v_exp_f32_e32 v98, v108
	v_exp_f32_e32 v99, v109
	v_pk_add_f32 v[110:111], v[110:111], v[48:49] op_sel_hi:[1,0] neg_lo:[0,1] neg_hi:[0,1]
	v_exp_f32_e32 v100, v110
	v_exp_f32_e32 v101, v111
	v_pk_add_f32 v[112:113], v[112:113], v[48:49] op_sel_hi:[1,0] neg_lo:[0,1] neg_hi:[0,1]
	v_exp_f32_e32 v102, v112
	v_exp_f32_e32 v103, v113
	v_sub_f32_e32 v0, v138, v48
	v_exp_f32_e32 v0, v0
	v_add_u32_e32 v104, s77, v133
	v_pk_add_f32 v[140:141], v[50:51], v[52:53]
	v_pk_add_f32 v[140:141], v[140:141], v[54:55]
	v_pk_add_f32 v[140:141], v[140:141], v[56:57]
	v_pk_add_f32 v[140:141], v[140:141], v[58:59]
	v_pk_add_f32 v[140:141], v[140:141], v[60:61]
	v_pk_add_f32 v[140:141], v[140:141], v[62:63]
	v_pk_add_f32 v[140:141], v[140:141], v[88:89]
	v_pk_add_f32 v[140:141], v[140:141], v[90:91]
	v_pk_add_f32 v[140:141], v[140:141], v[92:93]
	v_pk_add_f32 v[140:141], v[140:141], v[94:95]
	v_pk_add_f32 v[140:141], v[140:141], v[96:97]
	v_pk_add_f32 v[140:141], v[140:141], v[98:99]
	v_pk_add_f32 v[140:141], v[140:141], v[100:101]
	v_pk_add_f32 v[140:141], v[140:141], v[102:103]
	v_add_f32_e32 v10, v140, v141
	v_add_f32_e32 v10, v49, v10
	v_add_f32_e32 v10, v11, v10
	v_cvt_pk_bf16_f32 v12, v49, v51
	v_cvt_pk_bf16_f32 v13, v52, v53
	v_cvt_pk_bf16_f32 v14, v54, v50
	v_cvt_pk_bf16_f32 v15, v55, v11
	v_cvt_pk_bf16_f32 v50, v56, v57
	v_cvt_pk_bf16_f32 v51, v58, v59
	v_cvt_pk_bf16_f32 v52, v60, v61
	ds_read_b128 v[54:57], v104 offset:18432
	ds_read_b128 v[58:61], v104 offset:18464
	v_pk_mul_f32 v[46:47], v[46:47], v[0:1] op_sel_hi:[1,0]
	v_pk_mul_f32 v[44:45], v[44:45], v[0:1] op_sel_hi:[1,0]
	v_pk_mul_f32 v[42:43], v[42:43], v[0:1] op_sel_hi:[1,0]
	v_pk_mul_f32 v[40:41], v[40:41], v[0:1] op_sel_hi:[1,0]
	v_pk_mul_f32 v[38:39], v[38:39], v[0:1] op_sel_hi:[1,0]
	v_pk_mul_f32 v[36:37], v[36:37], v[0:1] op_sel_hi:[1,0]
	v_pk_mul_f32 v[34:35], v[34:35], v[0:1] op_sel_hi:[1,0]
	v_pk_mul_f32 v[32:33], v[32:33], v[0:1] op_sel_hi:[1,0]
	v_pk_mul_f32 v[30:31], v[30:31], v[0:1] op_sel_hi:[1,0]
	v_pk_mul_f32 v[28:29], v[28:29], v[0:1] op_sel_hi:[1,0]
	s_waitcnt lgkmcnt(1)
	v_mfma_f32_32x32x16_bf16 v[32:47], v[54:57], v[12:15], v[32:47]
	ds_read_b128 v[54:57], v104 offset:23040
	v_mul_f32_e64 v26, v26, v0
	v_mul_f32_e64 v27, v27, v0
	v_mul_f32_e64 v24, v24, v0
	v_mul_f32_e64 v25, v25, v0
	v_pk_mul_f32 v[22:23], v[22:23], v[0:1] op_sel_hi:[1,0]
	v_pk_mul_f32 v[20:21], v[20:21], v[0:1] op_sel_hi:[1,0]
	v_pk_mul_f32 v[18:19], v[18:19], v[0:1] op_sel_hi:[1,0]
	v_pk_mul_f32 v[16:17], v[16:17], v[0:1] op_sel_hi:[1,0]
	v_cvt_pk_bf16_f32 v53, v62, v63
	s_waitcnt lgkmcnt(0)
	v_mfma_f32_32x32x16_bf16 v[16:31], v[54:57], v[12:15], v[16:31]
	ds_read_b128 v[12:15], v104 offset:23072
	ds_read_b128 v[54:57], v104 offset:18496
	v_mfma_f32_32x32x16_bf16 v[32:47], v[58:61], v[50:53], v[32:47]
	s_waitcnt lgkmcnt(1)
	v_mfma_f32_32x32x16_bf16 v[16:31], v[12:15], v[50:53], v[16:31]
	v_cvt_pk_bf16_f32 v12, v88, v89
	v_cvt_pk_bf16_f32 v13, v90, v91
	v_cvt_pk_bf16_f32 v14, v92, v93
	v_cvt_pk_bf16_f32 v15, v94, v95
	v_cvt_pk_bf16_f32 v50, v96, v97
	v_cvt_pk_bf16_f32 v51, v98, v99
	v_cvt_pk_bf16_f32 v52, v100, v101
	s_waitcnt lgkmcnt(0)
	v_mfma_f32_32x32x16_bf16 v[32:47], v[54:57], v[12:15], v[32:47]
	ds_read_b128 v[54:57], v104 offset:18528
	v_cvt_pk_bf16_f32 v53, v102, v103
	s_waitcnt lgkmcnt(0)
	v_mfma_f32_32x32x16_bf16 v[32:47], v[54:57], v[50:53], v[32:47]
	ds_read_b128 v[54:57], v104 offset:23104
	v_fmac_f32_e32 v10, v137, v0
	v_mov_b32_e32 v138, v48
	v_mov_b32_e32 v137, v10
	s_waitcnt lgkmcnt(0)
	v_mfma_f32_32x32x16_bf16 v[16:31], v[54:57], v[12:15], v[16:31]
	ds_read_b128 v[12:15], v104 offset:23136
	s_waitcnt lgkmcnt(0)
	v_mfma_f32_32x32x16_bf16 v[16:31], v[12:15], v[50:53], v[16:31]
